# selected loop: LDS staging writes of the prefetched tile issued at the step head instead of in front of the step's barrier
# baseline (speedup 1.0000x reference)
.Lsel_nogl_0:
	s_add_u32 s1, s76, 2
	s_cmp_lt_u32 s1, s79
	s_cbranch_scc0 .Lsel_hns_0
	s_add_u32 s1, s76, 3
	s_cmp_lt_u32 s1, s79
	s_cbranch_scc1 .Lsel_hst2_0
	s_waitcnt vmcnt(0)
	s_branch .Lsel_hst_0

.Lsel_hst_0:
	v_add_u32_e32 v0, s83, v101
	ds_write_b128 v0, v[26:29]
	ds_write_b128 v0, v[96:99] offset:9216
.Lsel_hns_0:
	s_lshr_b32 s98, s86, 5
	s_and_b32 s98, s98, 3
	s_lshl_b32 s98, s98, 2
	v_add_u32_e32 v184, s98, v103
	ds_read_b32 v184, v184
	s_cmp_lg_u64 s[100:101], -1
	s_cbranch_scc0 .Lsel_noN_0
	s_cmp_lg_u64 s[72:73], -1
	s_cbranch_scc0 .Lsel_Nonly_0
	v_add_u32_e32 v0, s82, v208
	ds_read_b128 v[108:111], v0
	ds_read_b128 v[112:115], v0 offset:4608
	ds_read_b128 v[116:119], v0 offset:32
	ds_read_b128 v[120:123], v0 offset:4640
	s_add_u32 s1, s76, 1
	s_cmp_lg_u32 s1, s79
	s_cbranch_scc1 .Lsel_nodiag_0b
	v_cndmask_b32_e64 v80, v80, v185, s[6:7]
	v_cndmask_b32_e64 v64, v64, v185, s[8:9]
	v_cndmask_b32_e64 v81, v185, v81, s[10:11]
	v_cndmask_b32_e64 v65, v65, v185, s[12:13]
	v_cndmask_b32_e64 v82, v82, v185, s[14:15]
	v_cndmask_b32_e64 v66, v66, v185, s[16:17]
	v_cndmask_b32_e64 v83, v83, v185, s[18:19]
	v_cndmask_b32_e64 v67, v67, v185, s[20:21]
	v_cndmask_b32_e64 v84, v84, v185, s[22:23]
	v_cndmask_b32_e64 v68, v68, v185, s[24:25]
	v_cndmask_b32_e64 v85, v85, v185, s[26:27]
	v_cndmask_b32_e64 v69, v69, v185, s[28:29]
	v_cndmask_b32_e64 v86, v86, v185, s[30:31]
	v_cndmask_b32_e64 v70, v70, v185, s[34:35]
	v_cndmask_b32_e64 v87, v87, v185, s[36:37]
	v_cndmask_b32_e64 v71, v71, v185, s[38:39]
	v_cndmask_b32_e64 v88, v88, v185, s[40:41]
	v_cndmask_b32_e64 v72, v72, v185, s[42:43]
	v_cndmask_b32_e64 v89, v89, v185, s[44:45]
	v_cndmask_b32_e64 v73, v73, v185, s[46:47]
	v_cndmask_b32_e64 v90, v90, v185, s[48:49]
	v_cndmask_b32_e64 v74, v74, v185, s[50:51]
	v_cndmask_b32_e64 v91, v91, v185, s[52:53]
	v_cndmask_b32_e64 v75, v75, v185, s[54:55]
	v_cndmask_b32_e64 v92, v92, v185, s[56:57]
	v_cndmask_b32_e64 v76, v76, v185, s[58:59]
	v_cndmask_b32_e64 v93, v93, v185, s[60:61]
	v_cndmask_b32_e64 v77, v77, v185, s[62:63]
	v_cndmask_b32_e64 v94, v94, v185, s[64:65]
	v_cndmask_b32_e64 v78, v78, v185, s[66:67]
	v_cndmask_b32_e64 v95, v95, v185, s[68:69]
	v_cndmask_b32_e64 v79, v79, v185, s[70:71]

.Lsel_noresc_0c:
.Lsel_tail_0:
	s_waitcnt lgkmcnt(0)
	s_and_b32 s1, s86, 31
	v_bfe_u32 v184, v184, s1, 1
	v_cmp_eq_u32_e64 s[98:99], 0, v184
	v_mov_b32_e32 v0, s77
	ds_read_b32 v182, v0 offset:16
	s_add_u32 s1, s76, 2
	s_cmp_lt_u32 s1, s79
	s_cbranch_scc1 .Lsel_bar_0
	s_nop 4
	s_mov_b64 s[98:99], -1

.Lsel_hst_1:
	v_add_u32_e32 v0, s83, v101
	ds_write_b128 v0, v[18:21]
	ds_write_b128 v0, v[22:25] offset:9216
.Lsel_hns_1:
	s_lshr_b32 s98, s86, 5
	s_and_b32 s98, s98, 3
	s_lshl_b32 s98, s98, 2
	v_add_u32_e32 v184, s98, v103
	ds_read_b32 v184, v184
	s_cmp_lg_u64 s[100:101], -1
	s_cbranch_scc0 .Lsel_noN_1
	s_cmp_lg_u64 s[72:73], -1
	s_cbranch_scc0 .Lsel_Nonly_1
	v_add_u32_e32 v0, s82, v208
	ds_read_b128 v[108:111], v0
	ds_read_b128 v[112:115], v0 offset:4608
	ds_read_b128 v[116:119], v0 offset:32
	ds_read_b128 v[120:123], v0 offset:4640
	s_add_u32 s1, s76, 1
	s_cmp_lg_u32 s1, s79
	s_cbranch_scc1 .Lsel_nodiag_1b
	v_cndmask_b32_e64 v238, v238, v185, s[6:7]
	v_cndmask_b32_e64 v222, v222, v185, s[8:9]
	v_cndmask_b32_e64 v239, v185, v239, s[10:11]
	v_cndmask_b32_e64 v223, v223, v185, s[12:13]
	v_cndmask_b32_e64 v240, v240, v185, s[14:15]
	v_cndmask_b32_e64 v224, v224, v185, s[16:17]
	v_cndmask_b32_e64 v241, v241, v185, s[18:19]
	v_cndmask_b32_e64 v225, v225, v185, s[20:21]
	v_cndmask_b32_e64 v242, v242, v185, s[22:23]
	v_cndmask_b32_e64 v226, v226, v185, s[24:25]
	v_cndmask_b32_e64 v243, v243, v185, s[26:27]
	v_cndmask_b32_e64 v227, v227, v185, s[28:29]
	v_cndmask_b32_e64 v244, v244, v185, s[30:31]
	v_cndmask_b32_e64 v228, v228, v185, s[34:35]
	v_cndmask_b32_e64 v245, v245, v185, s[36:37]
	v_cndmask_b32_e64 v229, v229, v185, s[38:39]
	v_cndmask_b32_e64 v246, v246, v185, s[40:41]
	v_cndmask_b32_e64 v230, v230, v185, s[42:43]
	v_cndmask_b32_e64 v247, v247, v185, s[44:45]
	v_cndmask_b32_e64 v231, v231, v185, s[46:47]
	v_cndmask_b32_e64 v248, v248, v185, s[48:49]
	v_cndmask_b32_e64 v232, v232, v185, s[50:51]
	v_cndmask_b32_e64 v249, v249, v185, s[52:53]
	v_cndmask_b32_e64 v233, v233, v185, s[54:55]
	v_cndmask_b32_e64 v250, v250, v185, s[56:57]
	v_cndmask_b32_e64 v234, v234, v185, s[58:59]
	v_cndmask_b32_e64 v251, v251, v185, s[60:61]
	v_cndmask_b32_e64 v235, v235, v185, s[62:63]
	v_cndmask_b32_e64 v252, v252, v185, s[64:65]
	v_cndmask_b32_e64 v236, v236, v185, s[66:67]
	v_cndmask_b32_e64 v253, v253, v185, s[68:69]
	v_cndmask_b32_e64 v237, v237, v185, s[70:71]
